# x3 plus grid barrier leader publishes the XCD generation before its own L1 invalidate
# baseline (speedup 1.0000x reference)
; __device__ __forceinline__ unsigned xb_ld(unsigned* p)              { return __hip_atomic_load(p, __ATOMIC_RELAXED, __HIP_MEMORY_SCOPE_AGENT); }
; __device__ __forceinline__ unsigned xb_add(unsigned* p, unsigned v) { return __hip_atomic_fetch_add(p, v, __ATOMIC_RELAXED, __HIP_MEMORY_SCOPE_AGENT); }
; #define XB_SPIN(cond, bar) do { unsigned _sp = 0; while (cond) { __builtin_amdgcn_s_sleep(1); \
;     if ((++_sp & 255u) == 0u) { if (xb_ld(&(bar)[XB_TMO])) break; if (_sp > XB_SPIN_CAP) { atomicAdd(&(bar)[XB_TMO], 1u); break; } } } } while (0)
; __device__ __forceinline__ void xcd_barrier(const XcdBarrier& b) {
;     ...
;         if (old + 1u == (gen + 1u) * nloc) {
;             __builtin_amdgcn_fence(__ATOMIC_RELEASE, "agent");
;             asm volatile("s_waitcnt vmcnt(0)" ::: "memory");
;             const unsigned og = xb_add(&bar[XB_TOP], 1u);
;             const unsigned tg = og / nx;
;             if (og + 1u == (tg + 1u) * nx) xb_add(&bar[XB_TOPGEN], 1u);
;             else XB_SPIN(xb_ld(&bar[XB_TOPGEN]) == tg, bar);
;             __builtin_amdgcn_fence(__ATOMIC_ACQUIRE, "agent");
;             xb_add(&bar[XB_XGEN(b.x)], 1u);
;             asm volatile("s_waitcnt vmcnt(0)" ::: "memory");
.LBB0_101:
	s_or_b64 exec, exec, s[14:15]
	v_mov_b32_e32 v1, 0x2000
	v_mov_b32_e32 v2, 1
	s_waitcnt vmcnt(0)
	global_atomic_add v1, v2, s[6:7] offset:1024
	buffer_inv sc1
	s_waitcnt vmcnt(0)

; __device__ __forceinline__ unsigned xb_ld(unsigned* p)              { return __hip_atomic_load(p, __ATOMIC_RELAXED, __HIP_MEMORY_SCOPE_AGENT); }
; __device__ __forceinline__ unsigned xb_add(unsigned* p, unsigned v) { return __hip_atomic_fetch_add(p, v, __ATOMIC_RELAXED, __HIP_MEMORY_SCOPE_AGENT); }
; #define XB_SPIN(cond, bar) do { unsigned _sp = 0; while (cond) { __builtin_amdgcn_s_sleep(1); \
;     if ((++_sp & 255u) == 0u) { if (xb_ld(&(bar)[XB_TMO])) break; if (_sp > XB_SPIN_CAP) { atomicAdd(&(bar)[XB_TMO], 1u); break; } } } } while (0)
; __device__ __forceinline__ void xcd_barrier(const XcdBarrier& b) {
;     ...
;         if (old + 1u == (gen + 1u) * nloc) {
;             __builtin_amdgcn_fence(__ATOMIC_RELEASE, "agent");
;             asm volatile("s_waitcnt vmcnt(0)" ::: "memory");
;             const unsigned og = xb_add(&bar[XB_TOP], 1u);
;             const unsigned tg = og / nx;
;             if (og + 1u == (tg + 1u) * nx) xb_add(&bar[XB_TOPGEN], 1u);
;             else XB_SPIN(xb_ld(&bar[XB_TOPGEN]) == tg, bar);
;             __builtin_amdgcn_fence(__ATOMIC_ACQUIRE, "agent");
;             xb_add(&bar[XB_XGEN(b.x)], 1u);
;             asm volatile("s_waitcnt vmcnt(0)" ::: "memory");
.LBB0_369:
	s_or_b64 exec, exec, s[14:15]
	v_mov_b32_e32 v1, 0x2000
	v_mov_b32_e32 v2, 1
	s_waitcnt vmcnt(0)
	global_atomic_add v1, v2, s[4:5] offset:1024
	buffer_inv sc1
	s_waitcnt vmcnt(0)

; __device__ __forceinline__ unsigned xb_ld(unsigned* p)              { return __hip_atomic_load(p, __ATOMIC_RELAXED, __HIP_MEMORY_SCOPE_AGENT); }
; __device__ __forceinline__ unsigned xb_add(unsigned* p, unsigned v) { return __hip_atomic_fetch_add(p, v, __ATOMIC_RELAXED, __HIP_MEMORY_SCOPE_AGENT); }
; #define XB_SPIN(cond, bar) do { unsigned _sp = 0; while (cond) { __builtin_amdgcn_s_sleep(1); \
;     if ((++_sp & 255u) == 0u) { if (xb_ld(&(bar)[XB_TMO])) break; if (_sp > XB_SPIN_CAP) { atomicAdd(&(bar)[XB_TMO], 1u); break; } } } } while (0)
; __device__ __forceinline__ void xcd_barrier(const XcdBarrier& b) {
;     ...
;         if (old + 1u == (gen + 1u) * nloc) {
;             __builtin_amdgcn_fence(__ATOMIC_RELEASE, "agent");
;             asm volatile("s_waitcnt vmcnt(0)" ::: "memory");
;             const unsigned og = xb_add(&bar[XB_TOP], 1u);
;             const unsigned tg = og / nx;
;             if (og + 1u == (tg + 1u) * nx) xb_add(&bar[XB_TOPGEN], 1u);
;             else XB_SPIN(xb_ld(&bar[XB_TOPGEN]) == tg, bar);
;             __builtin_amdgcn_fence(__ATOMIC_ACQUIRE, "agent");
;             xb_add(&bar[XB_XGEN(b.x)], 1u);
;             asm volatile("s_waitcnt vmcnt(0)" ::: "memory");
.LBB0_471:
	s_or_b64 exec, exec, s[6:7]
	v_mov_b32_e32 v1, 0x2000
	v_mov_b32_e32 v2, 1
	s_waitcnt vmcnt(0)
	global_atomic_add v1, v2, s[4:5] offset:1024
	buffer_inv sc1
	s_waitcnt vmcnt(0)

; __device__ __forceinline__ unsigned xb_ld(unsigned* p)              { return __hip_atomic_load(p, __ATOMIC_RELAXED, __HIP_MEMORY_SCOPE_AGENT); }
; __device__ __forceinline__ unsigned xb_add(unsigned* p, unsigned v) { return __hip_atomic_fetch_add(p, v, __ATOMIC_RELAXED, __HIP_MEMORY_SCOPE_AGENT); }
; #define XB_SPIN(cond, bar) do { unsigned _sp = 0; while (cond) { __builtin_amdgcn_s_sleep(1); \
;     if ((++_sp & 255u) == 0u) { if (xb_ld(&(bar)[XB_TMO])) break; if (_sp > XB_SPIN_CAP) { atomicAdd(&(bar)[XB_TMO], 1u); break; } } } } while (0)
; __device__ __forceinline__ void xcd_barrier(const XcdBarrier& b) {
;     ...
;         if (old + 1u == (gen + 1u) * nloc) {
;             __builtin_amdgcn_fence(__ATOMIC_RELEASE, "agent");
;             asm volatile("s_waitcnt vmcnt(0)" ::: "memory");
;             const unsigned og = xb_add(&bar[XB_TOP], 1u);
;             const unsigned tg = og / nx;
;             if (og + 1u == (tg + 1u) * nx) xb_add(&bar[XB_TOPGEN], 1u);
;             else XB_SPIN(xb_ld(&bar[XB_TOPGEN]) == tg, bar);
;             __builtin_amdgcn_fence(__ATOMIC_ACQUIRE, "agent");
;             xb_add(&bar[XB_XGEN(b.x)], 1u);
;             asm volatile("s_waitcnt vmcnt(0)" ::: "memory");
.LBB0_474:
	s_or_b64 exec, exec, s[4:5]
	v_readlane_b32 s4, v245, 50
	v_readlane_b32 s5, v245, 51
	s_waitcnt vmcnt(0)
	s_nop 3
	global_atomic_add v3, v213, s[4:5]
	buffer_inv sc1
	s_waitcnt vmcnt(0)
